# v11 plus stacked small edits: sample-unit K swizzle fix, PV V-fragment reads re-pipelined, masked-tile fill only when masked, latent-phase gain vectors hoisted, scalar fma instead of packed fma in att
# speedup vs baseline: 1.0066x; 1.0066x over previous
.LBB0_369:
	s_cmp_lt_i32 s40, 4
	s_cselect_b64 s[8:9], -1, 0
	s_and_b64 s[8:9], s[8:9], s[6:7]
	s_andn2_b64 vcc, exec, s[8:9]
	s_cbranch_vccnz .LBB0_373
	v_mov_b32_e32 v0, v226
	s_lshl_b32 s3, s2, 3
	v_readfirstlane_b32 s6, v0
	s_ashr_i32 s6, s6, 6
	s_add_i32 s10, s6, s3
	s_cmp_gt_i32 s10, 0x81ff
	s_cbranch_scc1 .LBB0_373
	s_load_dwordx4 s[16:19], s[0:1], 0x68
	s_load_dwordx2 s[6:7], s[0:1], 0xa8
	v_and_b32_e32 v22, 63, v0
	v_lshlrev_b32_e32 v20, 2, v22
	v_mov_b32_e32 v21, 0
	s_ashr_i32 s11, s10, 31
	v_lshlrev_b32_e32 v16, 1, v22
	s_waitcnt lgkmcnt(0)
	v_lshl_add_u64 v[2:3], s[6:7], 0, v[20:21]
	s_lshl_b64 s[6:7], s[10:11], 7
	v_and_b32_e32 v1, 31, v0
	v_or_b32_e32 v6, s6, v16
	v_mov_b32_e32 v7, s7
	s_mov_b64 s[6:7], 0x15000000
	v_cvt_f32_ubyte0_e32 v1, v1
	v_lshlrev_b32_e32 v12, 3, v22
	v_lshl_add_u64 v[6:7], v[6:7], 0, s[6:7]
	s_lshl_b64 s[6:7], s[10:11], 9
	v_mul_f32_e32 v1, 0xbed49a78, v1
	v_or_b32_e32 v8, s6, v12
	v_mov_b32_e32 v9, s7
	s_mov_b64 s[6:7], 0xff00000
	s_mul_hi_i32 s3, s10, 0x300
	v_exp_f32_e32 v18, v1
	v_mov_b32_e32 v13, v21
	v_lshl_add_u64 v[8:9], v[8:9], 0, s[6:7]
	s_mul_i32 s6, s10, 0x300
	v_mov_b32_e32 v11, s3
	s_mul_hi_i32 s3, s10, 0x600
	s_mul_i32 s22, s10, 0x600
	s_lshl_b32 s12, s42, 3
	v_lshl_add_u64 v[4:5], s[16:17], 0, v[12:13]
	v_or_b32_e32 v10, s6, v20
	v_or_b32_e32 v12, s22, v12
	v_mov_b32_e32 v13, s3
	s_mov_b64 s[6:7], 0x8400300
	v_lshlrev_b32_e32 v0, 4, v22
	v_mov_b32_e32 v1, v21
	s_ashr_i32 s13, s12, 31
	v_lshl_add_u64 v[14:15], v[12:13], 0, s[6:7]
	v_or_b32_e32 v16, s22, v16
	v_mov_b32_e32 v17, s3
	s_mov_b64 s[6:7], 0x8400500
	v_lshl_add_u64 v[0:1], s[18:19], 0, v[0:1]
	v_cmp_gt_u32_e32 vcc, 32, v22
	s_lshl_b64 s[14:15], s[12:13], 7
	s_lshl_b64 s[16:17], s[12:13], 9
	s_mul_i32 s18, s42, 0x1800
	s_mul_hi_i32 s19, s12, 0x300
	s_mul_i32 s20, s42, 0x3000
	s_mul_hi_i32 s21, s12, 0x600
	v_or_b32_e32 v12, s22, v20
	v_lshl_add_u64 v[16:17], v[16:17], 0, s[6:7]
	s_mov_b32 s3, 0xa200000
	s_mov_b32 s22, 0x8200000
	s_mov_b32 s23, 0x8400000
	v_mov_b32_e32 v19, 0x358637bd
	s_mov_b32 s24, 0xe600000
	v_lshlrev_b32_e32 v20, 2, v20
	v_lshlrev_b32_e32 v21, 2, v22
	global_load_dwordx2 v[42:43], v[4:5], off
	global_load_dwordx2 v[44:45], v[4:5], off offset:512
	global_load_dwordx2 v[46:47], v[4:5], off offset:1024
	global_load_dwordx4 v[48:51], v[0:1], off
	global_load_dword v52, v[2:3], off
.LBB0_372:
	v_lshl_add_u64 v[22:23], s[38:39], 0, v[12:13]
	v_add_co_u32_e64 v22, s[6:7], s23, v22
	v_lshl_add_u64 v[26:27], s[38:39], 0, v[16:17]
	s_nop 0
	v_addc_co_u32_e64 v23, s[6:7], 0, v23, s[6:7]
	global_load_dword v32, v[22:23], off
	global_load_dword v33, v[22:23], off offset:256
	global_load_dword v34, v[22:23], off offset:512
	v_lshl_add_u64 v[22:23], s[38:39], 0, v[14:15]
	global_load_dwordx2 v[30:31], v[22:23], off
	global_load_ushort v40, v[26:27], off
	v_lshl_add_u64 v[28:29], s[38:39], 0, v[10:11]
	v_add_co_u32_e64 v28, s[6:7], s24, v28
	v_lshl_add_u64 v[10:11], v[10:11], 0, s[18:19]
	s_nop 0
	v_addc_co_u32_e64 v29, s[6:7], 0, v29, s[6:7]
	s_and_b32 s6, s10, 0xfff
	s_and_b32 s7, s10, 15
	s_cmp_lt_i32 s10, 0x8000
	s_cselect_b32 s25, s3, 0xaa80000
	s_bitset1_b32 s7, 12
	s_cmp_lt_i32 s10, 0x8000
	s_cselect_b32 s26, s22, 0xaa00000
	s_cselect_b32 s28, s6, s7
	s_add_i32 s6, s10, 0xffff8000
	s_cmp_lt_i32 s10, 0x8000
	s_cselect_b32 s7, s11, 0
	s_cselect_b32 s6, s10, s6
	s_add_u32 s29, s36, s26
	s_addc_u32 s30, s37, 0
	s_lshl_b64 s[26:27], s[6:7], 10
	s_add_u32 s26, s29, s26
	s_addc_u32 s27, s30, s27
	s_add_u32 s25, s36, s25
	v_lshl_add_u64 v[14:15], v[14:15], 0, s[20:21]
	v_lshl_add_u64 v[12:13], v[12:13], 0, s[20:21]
	v_lshl_add_u64 v[16:17], v[16:17], 0, s[20:21]
	s_waitcnt vmcnt(0)
	v_lshlrev_b32_e32 v22, 16, v32
	v_and_b32_e32 v23, 0xffff0000, v32
	v_lshlrev_b32_e32 v26, 16, v33
	v_and_b32_e32 v27, 0xffff0000, v33
	v_lshlrev_b32_e32 v32, 16, v34
	v_and_b32_e32 v33, 0xffff0000, v34
	v_pk_mul_f32 v[34:35], v[22:23], v[22:23]
	v_pk_mul_f32 v[36:37], v[26:27], v[26:27]
	v_pk_mul_f32 v[38:39], v[32:33], v[32:33]
	v_add_f32_e32 v36, v36, v37
	v_add_f32_e32 v34, v34, v35
	v_add_f32_e32 v35, v38, v39
	v_add_f32_e32 v34, v34, v36
	v_add_f32_e32 v34, v34, v35
	ds_swizzle_b32 v35, v34 offset:swizzle(SWAP,1)
	s_waitcnt lgkmcnt(0)
	v_add_f32_e32 v34, v34, v35
	ds_swizzle_b32 v35, v34 offset:swizzle(SWAP,2)
	s_waitcnt lgkmcnt(0)
	v_add_f32_e32 v34, v34, v35
	ds_swizzle_b32 v35, v34 offset:swizzle(SWAP,4)
	s_waitcnt lgkmcnt(0)
	v_add_f32_e32 v34, v34, v35
	ds_swizzle_b32 v35, v34 offset:swizzle(SWAP,8)
	s_waitcnt lgkmcnt(0)
	v_add_f32_e32 v34, v34, v35
	ds_swizzle_b32 v35, v34 offset:swizzle(SWAP,16)
	s_waitcnt lgkmcnt(0)
	v_add_f32_e32 v34, v34, v35
	v_mov_b32_e32 v35, v34
	s_nop 1
	v_permlane32_swap_b32_e32 v34, v35
	v_add_f32_e32 v34, v34, v35
	v_fmamk_f32 v34, v34, 0x3b2aaaab, v19
	v_rsq_f32_e32 v34, v34
	s_nop 0
	v_pk_mul_f32 v[22:23], v[34:35], v[22:23] op_sel_hi:[0,1]
	v_pk_mul_f32 v[22:23], v[22:23], v[42:43]
	v_pk_mul_f32 v[24:25], v[34:35], v[26:27] op_sel_hi:[0,1]
	v_cvt_pk_bf16_f32 v22, v22, v23
	global_store_dword v[28:29], v22, off
	v_lshl_add_u64 v[26:27], s[38:39], 0, v[8:9]
	v_lshl_add_u64 v[8:9], v[8:9], 0, s[16:17]
	v_pk_mul_f32 v[22:23], v[24:25], v[44:45]
	s_nop 0
	v_cvt_pk_bf16_f32 v22, v22, v23
	global_store_dword v[28:29], v22, off offset:256
	v_pk_mul_f32 v[24:25], v[34:35], v[32:33] op_sel_hi:[0,1]
	v_pk_mul_f32 v[22:23], v[24:25], v[46:47]
	s_nop 0
	v_cvt_pk_bf16_f32 v22, v22, v23
	global_store_dword v[28:29], v22, off offset:512
	v_lshlrev_b32_e32 v28, 16, v30
	v_and_b32_e32 v29, 0xffff0000, v30
	v_lshlrev_b32_e32 v30, 16, v31
	v_and_b32_e32 v31, 0xffff0000, v31
	v_mul_f32_e32 v32, v29, v29
	v_mul_f32_e32 v33, v31, v31
	v_fmac_f32_e32 v32, v28, v28
	v_fmac_f32_e32 v33, v30, v30
	v_add_f32_e32 v32, v32, v33
	ds_swizzle_b32 v33, v32 offset:swizzle(SWAP,1)
	s_waitcnt lgkmcnt(0)
	v_add_f32_e32 v32, v32, v33
	ds_swizzle_b32 v33, v32 offset:swizzle(SWAP,2)
	s_waitcnt lgkmcnt(0)
	v_add_f32_e32 v32, v32, v33
	ds_swizzle_b32 v33, v32 offset:swizzle(SWAP,4)
	s_waitcnt lgkmcnt(0)
	v_add_f32_e32 v32, v32, v33
	ds_swizzle_b32 v33, v32 offset:swizzle(SWAP,8)
	s_waitcnt lgkmcnt(0)
	v_add_f32_e32 v32, v32, v33
	ds_swizzle_b32 v33, v32 offset:swizzle(SWAP,16)
	s_waitcnt lgkmcnt(0)
	v_add_f32_e32 v32, v32, v33
	v_mov_b32_e32 v33, v32
	s_nop 1
	v_permlane32_swap_b32_e32 v32, v33
	v_add_f32_e32 v32, v32, v33
	v_fmamk_f32 v32, v32, 0x3b800000, v19
	v_rsq_f32_e32 v32, v32
	s_nop 0
	v_pk_mul_f32 v[30:31], v[30:31], v[32:33] op_sel_hi:[1,0]
	v_pk_mul_f32 v[28:29], v[28:29], v[32:33] op_sel_hi:[1,0]
	v_pk_mul_f32 v[24:25], v[30:31], v[50:51]
	v_pk_mul_f32 v[22:23], v[28:29], v[48:49]
	global_store_dwordx4 v20, v[22:25], s[26:27]
	s_addc_u32 s26, s37, 0
	s_lshl_b64 s[6:7], s[6:7], 8
	v_cvt_pk_bf16_f32 v22, v22, v23
	v_cvt_pk_bf16_f32 v23, v24, v25
	global_store_dwordx2 v[26:27], v[22:23], off
	v_lshlrev_b32_e32 v27, 16, v40
	v_mul_f32_e32 v28, v27, v27
	ds_swizzle_b32 v28, v28 offset:swizzle(SWAP,1)
	v_cvt_f32_u32_e32 v25, s28
	s_add_u32 s6, s25, s6
	s_addc_u32 s7, s26, s7
	s_add_u32 s10, s10, s12
	s_waitcnt lgkmcnt(0)
	v_fmac_f32_e32 v28, v27, v27
	ds_swizzle_b32 v29, v28 offset:swizzle(SWAP,2)
	v_mul_f32_e32 v25, v18, v25
	v_mul_f32_e32 v26, 0.15915494, v25
	v_floor_f32_e32 v26, v26
	v_fma_f32 v25, v25, 0.15915494, -v26
	s_waitcnt lgkmcnt(0)
	v_add_f32_e32 v28, v28, v29
	ds_swizzle_b32 v29, v28 offset:swizzle(SWAP,4)
	v_sin_f32_e32 v26, v25
	v_cos_f32_e32 v25, v25
	s_addc_u32 s11, s11, s13
	v_lshl_add_u64 v[22:23], s[38:39], 0, v[6:7]
	s_waitcnt lgkmcnt(0)
	v_add_f32_e32 v28, v28, v29
	ds_swizzle_b32 v29, v28 offset:swizzle(SWAP,8)
	v_lshl_add_u64 v[6:7], v[6:7], 0, s[14:15]
	s_cmp_lt_i32 s10, 0x8200
	s_waitcnt lgkmcnt(0)
	v_add_f32_e32 v28, v28, v29
	ds_swizzle_b32 v29, v28 offset:swizzle(SWAP,16)
	s_waitcnt lgkmcnt(0)
	v_add_f32_e32 v28, v28, v29
	v_mov_b32_e32 v29, v28
	s_nop 1
	v_permlane32_swap_b32_e32 v28, v29
	v_add_f32_e32 v28, v28, v29
	v_fmamk_f32 v28, v28, 0x3c800000, v19
	v_rsq_f32_e32 v28, v28
	s_nop 0
	v_mul_f32_e32 v27, v28, v27
	v_mul_f32_e32 v24, v27, v52
	v_mov_b32_e32 v27, v24
	v_mov_b32_e32 v28, v24
	s_nop 1
	v_permlane32_swap_b32_e32 v27, v28
	v_cndmask_b32_e32 v27, v27, v28, vcc
	v_mul_f32_e32 v26, v26, v27
	v_cndmask_b32_e64 v26, v26, -v26, vcc
	v_fmac_f32_e32 v26, v25, v24
	v_cvt_pk_bf16_f32 v24, v26, s0
	global_store_dword v21, v26, s[6:7]
	global_store_short v[22:23], v24, off
	s_cbranch_scc1 .LBB0_372

.LBB0_701:
	s_add_i32 s17, s91, -1
	v_cmp_le_i32_e64 s[10:11], s17, v193
	s_and_saveexec_b64 s[12:13], s[10:11]
	s_cbranch_execnz .Lmy_qk1_vis
	s_or_b64 exec, exec, s[12:13]
	v_mov_b32_e32 v66, 0xf149f2ca
	v_mov_b32_e32 v67, 0xf149f2ca
	v_mov_b32_e32 v68, 0xf149f2ca
	v_mov_b32_e32 v69, 0xf149f2ca
	v_mov_b32_e32 v70, 0xf149f2ca
	v_mov_b32_e32 v71, 0xf149f2ca
	v_mov_b32_e32 v72, 0xf149f2ca
	v_mov_b32_e32 v73, 0xf149f2ca
	v_mov_b32_e32 v74, 0xf149f2ca
	v_mov_b32_e32 v75, 0xf149f2ca
	v_mov_b32_e32 v76, 0xf149f2ca
	v_mov_b32_e32 v77, 0xf149f2ca
	v_mov_b32_e32 v78, 0xf149f2ca
	v_mov_b32_e32 v79, 0xf149f2ca
	v_mov_b32_e32 v80, 0xf149f2ca
	v_mov_b32_e32 v81, 0xf149f2ca
	v_mov_b32_e32 v82, 0xf149f2ca
	v_mov_b32_e32 v83, 0xf149f2ca
	v_mov_b32_e32 v84, 0xf149f2ca
	v_mov_b32_e32 v85, 0xf149f2ca
	v_mov_b32_e32 v86, 0xf149f2ca
	v_mov_b32_e32 v87, 0xf149f2ca
	v_mov_b32_e32 v88, 0xf149f2ca
	v_mov_b32_e32 v89, 0xf149f2ca
	v_mov_b32_e32 v90, 0xf149f2ca
	v_mov_b32_e32 v91, 0xf149f2ca
	v_mov_b32_e32 v92, 0xf149f2ca
	v_mov_b32_e32 v93, 0xf149f2ca
	v_mov_b32_e32 v94, 0xf149f2ca
	v_mov_b32_e32 v95, 0xf149f2ca
	v_mov_b32_e32 v96, 0xf149f2ca
	v_mov_b32_e32 v97, 0xf149f2ca
	s_branch .LBB0_703
.Lmy_qk1_vis:
	ds_read_b128 v[202:205], v185 offset:57344
	ds_read_b128 v[206:209], v198 offset:12288
	ds_read_b128 v[210:213], v186 offset:57344
	ds_read_b128 v[214:217], v196 offset:12288
	ds_read_b128 v[218:221], v188 offset:57344
	ds_read_b128 v[222:225], v197 offset:12288
	s_waitcnt lgkmcnt(5)
	v_mfma_f32_32x32x16_bf16 v[82:97], v[202:205], v[126:129], 0
	ds_read_b128 v[228:231], v187 offset:57344
	s_waitcnt lgkmcnt(5)
	v_mfma_f32_32x32x16_bf16 v[66:81], v[206:209], v[126:129], 0
	ds_read_b128 v[202:205], v195 offset:12288
	s_waitcnt lgkmcnt(5)
	v_mfma_f32_32x32x16_bf16 v[82:97], v[210:213], v[122:125], v[82:97]
	ds_read_b128 v[206:209], v185 offset:57472
	s_waitcnt lgkmcnt(5)
	v_mfma_f32_32x32x16_bf16 v[66:81], v[214:217], v[122:125], v[66:81]
	ds_read_b128 v[210:213], v198 offset:12416
	s_waitcnt lgkmcnt(5)
	v_mfma_f32_32x32x16_bf16 v[82:97], v[218:221], v[118:121], v[82:97]
	ds_read_b128 v[214:217], v186 offset:57472
	s_waitcnt lgkmcnt(5)
	v_mfma_f32_32x32x16_bf16 v[66:81], v[222:225], v[118:121], v[66:81]
	ds_read_b128 v[218:221], v196 offset:12416
	s_waitcnt lgkmcnt(5)
	v_mfma_f32_32x32x16_bf16 v[82:97], v[228:231], v[114:117], v[82:97]
	ds_read_b128 v[222:225], v188 offset:57472
	s_waitcnt lgkmcnt(5)
	v_mfma_f32_32x32x16_bf16 v[66:81], v[202:205], v[114:117], v[66:81]
	ds_read_b128 v[228:231], v197 offset:12416
	ds_read_b128 v[232:235], v183
	s_waitcnt lgkmcnt(6)
	v_mfma_f32_32x32x16_bf16 v[82:97], v[206:209], v[110:113], v[82:97]
	ds_read_b128 v[202:205], v187 offset:57472
	s_waitcnt lgkmcnt(6)
	v_mfma_f32_32x32x16_bf16 v[66:81], v[210:213], v[110:113], v[66:81]
	ds_read_b128 v[206:209], v195 offset:12416
	ds_read_b128 v[236:239], v183 offset:32
	s_waitcnt lgkmcnt(7)
	v_mfma_f32_32x32x16_bf16 v[82:97], v[214:217], v[106:109], v[82:97]
	ds_read_b128 v[210:213], v185 offset:57600
	s_waitcnt lgkmcnt(7)
	v_mfma_f32_32x32x16_bf16 v[66:81], v[218:221], v[106:109], v[66:81]
	ds_read_b128 v[214:217], v198 offset:12544
	ds_read_b128 v[240:243], v183 offset:64
	s_waitcnt lgkmcnt(8)
	v_mfma_f32_32x32x16_bf16 v[82:97], v[222:225], v[102:105], v[82:97]
	ds_read_b128 v[218:221], v186 offset:57600
	s_waitcnt lgkmcnt(8)
	v_mfma_f32_32x32x16_bf16 v[66:81], v[228:231], v[102:105], v[66:81]
	ds_read_b128 v[222:225], v196 offset:12544
	s_waitcnt lgkmcnt(7)
	v_mfma_f32_32x32x16_bf16 v[82:97], v[202:205], v[98:101], v[82:97]
	ds_read_b128 v[228:231], v188 offset:57600
	s_waitcnt lgkmcnt(7)
	v_mfma_f32_32x32x16_bf16 v[66:81], v[206:209], v[98:101], v[66:81]
	ds_read_b128 v[202:205], v197 offset:12544
	s_waitcnt lgkmcnt(6)
	v_mfma_f32_32x32x16_bf16 v[82:97], v[210:213], v[232:235], v[82:97]
	ds_read_b128 v[206:209], v187 offset:57600
	s_waitcnt lgkmcnt(6)
	v_mfma_f32_32x32x16_bf16 v[66:81], v[214:217], v[232:235], v[66:81]
	ds_read_b128 v[210:213], v195 offset:12544
	ds_read_b128 v[232:235], v183 offset:96
	s_waitcnt lgkmcnt(6)
	v_mfma_f32_32x32x16_bf16 v[82:97], v[218:221], v[236:239], v[82:97]
	s_waitcnt lgkmcnt(5)
	v_mfma_f32_32x32x16_bf16 v[66:81], v[222:225], v[236:239], v[66:81]
	s_waitcnt lgkmcnt(4)
	v_mfma_f32_32x32x16_bf16 v[82:97], v[228:231], v[240:243], v[82:97]
	s_waitcnt lgkmcnt(3)
	v_mfma_f32_32x32x16_bf16 v[66:81], v[202:205], v[240:243], v[66:81]
	s_waitcnt lgkmcnt(0)
	v_mfma_f32_32x32x16_bf16 v[82:97], v[206:209], v[232:235], v[82:97]
	s_waitcnt lgkmcnt(0)
	v_mfma_f32_32x32x16_bf16 v[66:81], v[210:213], v[232:235], v[66:81]
.LBB0_703:
	s_or_b64 exec, exec, s[12:13]
	v_add_f32_e32 v150, 0, v146
	v_add_f32_e32 v150, v147, v150
	v_add_f32_e32 v150, v148, v150
	v_add_f32_e32 v150, v149, v150
	v_add_f32_e32 v150, v154, v150
	v_add_f32_e32 v150, v160, v150
	v_add_f32_e32 v150, v161, v150
	v_add_f32_e32 v150, v162, v150
	v_add_f32_e32 v150, v151, v150
	v_add_f32_e32 v150, v152, v150
	v_add_f32_e32 v150, v153, v150
	v_add_f32_e32 v150, v155, v150
	v_exp_f32_e32 v138, v138
	v_add_f32_e32 v150, v156, v150
	v_exp_f32_e32 v139, v139
	v_add_f32_e32 v150, v157, v150
	v_exp_f32_e32 v136, v136
	v_add_f32_e32 v150, v158, v150
	v_exp_f32_e32 v137, v137
	v_add_f32_e32 v150, v159, v150
	v_exp_f32_e32 v134, v134
	v_add_f32_e32 v150, v138, v150
	v_exp_f32_e32 v135, v135
	v_add_f32_e32 v150, v139, v150
	v_exp_f32_e32 v132, v132
	v_add_f32_e32 v150, v136, v150
	v_exp_f32_e32 v133, v133
	v_add_f32_e32 v150, v137, v150
	v_exp_f32_e32 v130, v130
	v_add_f32_e32 v150, v134, v150
	v_exp_f32_e32 v131, v131
	v_add_f32_e32 v150, v135, v150
	v_exp_f32_e32 v144, v144
	v_add_f32_e32 v150, v132, v150
	v_exp_f32_e32 v145, v145
	v_add_f32_e32 v150, v133, v150
	v_exp_f32_e32 v142, v142
	v_add_f32_e32 v150, v130, v150
	v_exp_f32_e32 v143, v143
	v_add_f32_e32 v150, v131, v150
	v_exp_f32_e32 v140, v140
	v_add_f32_e32 v150, v144, v150
	v_exp_f32_e32 v141, v141
	v_add_f32_e32 v150, v145, v150
	v_add_f32_e32 v150, v142, v150
	v_add_f32_e32 v150, v143, v150
	v_add_f32_e32 v150, v140, v150
	v_add_f32_e32 v202, v141, v150
	v_mov_b32_e32 v203, v202
	v_cvt_pk_bf16_f32 v146, v146, v147
	v_cvt_pk_bf16_f32 v147, v148, v149
	v_cvt_pk_bf16_f32 v148, v154, v160
	v_cvt_pk_bf16_f32 v149, v161, v162
	v_cvt_pk_bf16_f32 v154, v151, v152
	v_cvt_pk_bf16_f32 v155, v153, v155
	v_cvt_pk_bf16_f32 v156, v156, v157
	v_cvt_pk_bf16_f32 v157, v158, v159
	v_cvt_pk_bf16_f32 v158, v138, v139
	v_cvt_pk_bf16_f32 v159, v136, v137
	v_cvt_pk_bf16_f32 v160, v134, v135
	v_cvt_pk_bf16_f32 v161, v132, v133
	v_cvt_pk_bf16_f32 v162, v130, v131
	v_cvt_pk_bf16_f32 v163, v144, v145
	v_cvt_pk_bf16_f32 v164, v142, v143
	v_cvt_pk_bf16_f32 v165, v140, v141
	v_permlane32_swap_b32_e32 v202, v203
	v_permlane32_swap_b32_e32 v146, v148
	v_permlane32_swap_b32_e32 v147, v149
	v_permlane32_swap_b32_e32 v154, v156
	v_permlane32_swap_b32_e32 v155, v157
	v_permlane32_swap_b32_e32 v158, v160
	v_permlane32_swap_b32_e32 v159, v161
	v_permlane32_swap_b32_e32 v162, v164
	v_permlane32_swap_b32_e32 v163, v165
	v_add_u32_e32 v205, s16, v172
	v_add_u32_e32 v130, 0x80, v205
	v_add_u32_e32 v132, 0xa0, v205
	v_add_u32_e32 v207, s16, v176
	v_ashrrev_i32_e32 v131, 31, v130
	v_ashrrev_i32_e32 v133, 31, v132
	v_add_u32_e32 v150, 0x80, v207
	v_lshlrev_b64 v[138:139], 11, v[130:131]
	v_lshlrev_b32_e32 v206, 1, v174
	v_lshlrev_b64 v[140:141], 11, v[132:133]
	v_ashrrev_i32_e32 v151, 31, v150
	v_or_b32_e32 v138, v138, v206
	v_or_b32_e32 v140, v140, v206
	v_lshlrev_b64 v[150:151], 7, v[150:151]
	v_lshl_add_u64 v[130:131], s[14:15], 0, v[138:139]
	v_lshl_add_u64 v[134:135], s[14:15], 0, v[140:141]
	v_lshl_add_u64 v[138:139], s[64:65], 0, v[138:139]
	v_lshl_add_u64 v[142:143], s[64:65], 0, v[140:141]
	v_lshl_add_u64 v[150:151], v[178:179], 0, v[150:151]
	global_load_dwordx4 v[130:133], v[130:131], off
	s_nop 0
	global_load_dwordx4 v[134:137], v[134:135], off
	s_nop 0
	global_load_dwordx4 v[138:141], v[138:139], off
	s_nop 0
	global_load_dwordx4 v[142:145], v[142:143], off
	s_nop 0
	global_load_dwordx4 v[150:153], v[150:151], off
	v_cmp_le_i32_e32 vcc, s17, v200
	s_and_saveexec_b64 s[12:13], vcc
	s_cbranch_execz .LBB0_705
	ds_read_b64_tr_b16 v[208:209], v182
	ds_read_b64_tr_b16 v[210:211], v182 offset:2048
	ds_read_b64_tr_b16 v[212:213], v182 offset:4096
	ds_read_b64_tr_b16 v[214:215], v182 offset:6144
	ds_read_b64_tr_b16 v[216:217], v182 offset:8192
	ds_read_b64_tr_b16 v[218:219], v182 offset:10240
	ds_read_b64_tr_b16 v[220:221], v182 offset:12288
	ds_read_b64_tr_b16 v[222:223], v182 offset:14336
	s_waitcnt lgkmcnt(6)
	s_nop 0
	v_mfma_f32_32x32x16_bf16 v[2:17], v[146:149], v[208:211], v[2:17]
	ds_read_b64_tr_b16 v[228:229], v182 offset:512
	ds_read_b64_tr_b16 v[230:231], v182 offset:2560
	s_waitcnt lgkmcnt(6)
	v_mfma_f32_32x32x16_bf16 v[2:17], v[154:157], v[212:215], v[2:17]
	ds_read_b64_tr_b16 v[208:209], v182 offset:4608
	ds_read_b64_tr_b16 v[210:211], v182 offset:6656
	s_waitcnt lgkmcnt(6)
	v_mfma_f32_32x32x16_bf16 v[2:17], v[158:161], v[216:219], v[2:17]
	ds_read_b64_tr_b16 v[212:213], v182 offset:8704
	ds_read_b64_tr_b16 v[214:215], v182 offset:10752
	s_waitcnt lgkmcnt(6)
	v_mfma_f32_32x32x16_bf16 v[2:17], v[162:165], v[220:223], v[2:17]
	ds_read_b64_tr_b16 v[216:217], v182 offset:12800
	ds_read_b64_tr_b16 v[218:219], v182 offset:14848
	s_waitcnt lgkmcnt(6)
	v_mfma_f32_32x32x16_bf16 v[50:65], v[146:149], v[228:231], v[50:65]
	ds_read_b64_tr_b16 v[220:221], v182 offset:1024
	ds_read_b64_tr_b16 v[222:223], v182 offset:3072
	s_waitcnt lgkmcnt(6)
	v_mfma_f32_32x32x16_bf16 v[50:65], v[154:157], v[208:211], v[50:65]
	ds_read_b64_tr_b16 v[228:229], v182 offset:5120
	ds_read_b64_tr_b16 v[230:231], v182 offset:7168
	s_waitcnt lgkmcnt(6)
	v_mfma_f32_32x32x16_bf16 v[50:65], v[158:161], v[212:215], v[50:65]
	ds_read_b64_tr_b16 v[208:209], v182 offset:9216
	ds_read_b64_tr_b16 v[210:211], v182 offset:11264
	s_waitcnt lgkmcnt(6)
	v_mfma_f32_32x32x16_bf16 v[50:65], v[162:165], v[216:219], v[50:65]
	ds_read_b64_tr_b16 v[212:213], v182 offset:13312
	ds_read_b64_tr_b16 v[214:215], v182 offset:15360
	s_waitcnt lgkmcnt(6)
	v_mfma_f32_32x32x16_bf16 v[34:49], v[146:149], v[220:223], v[34:49]
	ds_read_b64_tr_b16 v[216:217], v182 offset:1536
	ds_read_b64_tr_b16 v[218:219], v182 offset:3584
	s_waitcnt lgkmcnt(6)
	v_mfma_f32_32x32x16_bf16 v[34:49], v[154:157], v[228:231], v[34:49]
	ds_read_b64_tr_b16 v[220:221], v182 offset:5632
	ds_read_b64_tr_b16 v[222:223], v182 offset:7680
	s_waitcnt lgkmcnt(6)
	v_mfma_f32_32x32x16_bf16 v[34:49], v[158:161], v[208:211], v[34:49]
	ds_read_b64_tr_b16 v[228:229], v182 offset:9728
	ds_read_b64_tr_b16 v[230:231], v182 offset:11776
	s_waitcnt lgkmcnt(6)
	v_mfma_f32_32x32x16_bf16 v[34:49], v[162:165], v[212:215], v[34:49]
	ds_read_b64_tr_b16 v[208:209], v182 offset:13824
	ds_read_b64_tr_b16 v[210:211], v182 offset:15872
	s_waitcnt lgkmcnt(6)
	v_mfma_f32_32x32x16_bf16 v[18:33], v[146:149], v[216:219], v[18:33]
	s_waitcnt lgkmcnt(4)
	v_mfma_f32_32x32x16_bf16 v[18:33], v[154:157], v[220:223], v[18:33]
	s_waitcnt lgkmcnt(2)
	v_mfma_f32_32x32x16_bf16 v[18:33], v[158:161], v[228:231], v[18:33]
	s_waitcnt lgkmcnt(0)
	v_mfma_f32_32x32x16_bf16 v[18:33], v[162:165], v[208:211], v[18:33]

.LBB0_709:
	v_cndmask_b32_e64 v201, v146, v201, s[12:13]
	v_mul_f32_e32 v140, 0xbdd53b94, v201
	v_fmamk_f32 v82, v82, 0x3dd53b94, v140
	v_fmamk_f32 v83, v83, 0x3dd53b94, v140
	v_fmamk_f32 v84, v84, 0x3dd53b94, v140
	v_fmamk_f32 v85, v85, 0x3dd53b94, v140
	v_fmamk_f32 v86, v86, 0x3dd53b94, v140
	v_fmamk_f32 v87, v87, 0x3dd53b94, v140
	v_fmamk_f32 v88, v88, 0x3dd53b94, v140
	v_fmamk_f32 v89, v89, 0x3dd53b94, v140
	v_fmamk_f32 v90, v90, 0x3dd53b94, v140
	v_fmamk_f32 v91, v91, 0x3dd53b94, v140
	v_fmamk_f32 v92, v92, 0x3dd53b94, v140
	v_fmamk_f32 v93, v93, 0x3dd53b94, v140
	v_fmamk_f32 v94, v94, 0x3dd53b94, v140
	v_fmamk_f32 v95, v95, 0x3dd53b94, v140
	v_fmamk_f32 v96, v96, 0x3dd53b94, v140
	v_fmamk_f32 v97, v97, 0x3dd53b94, v140
	v_exp_f32_e32 v133, v82
	v_exp_f32_e32 v136, v83
	v_exp_f32_e32 v137, v84
	v_exp_f32_e32 v141, v85
	v_exp_f32_e32 v142, v86
	v_exp_f32_e32 v144, v87
	v_exp_f32_e32 v145, v88
	v_exp_f32_e32 v146, v89
	v_exp_f32_e32 v130, v90
	v_exp_f32_e32 v131, v91
	v_exp_f32_e32 v132, v92
	v_exp_f32_e32 v134, v93
	v_exp_f32_e32 v135, v94
	v_exp_f32_e32 v138, v95
	v_exp_f32_e32 v139, v96
	v_exp_f32_e32 v143, v97
	v_fmamk_f32 v147, v66, 0x3dd53b94, v140
	v_fmamk_f32 v148, v67, 0x3dd53b94, v140
	v_fmamk_f32 v149, v68, 0x3dd53b94, v140
	v_fmamk_f32 v150, v69, 0x3dd53b94, v140
	v_fmamk_f32 v151, v70, 0x3dd53b94, v140
	v_fmamk_f32 v152, v71, 0x3dd53b94, v140
	v_fmamk_f32 v153, v72, 0x3dd53b94, v140
	v_fmamk_f32 v154, v73, 0x3dd53b94, v140
	v_fmamk_f32 v155, v74, 0x3dd53b94, v140
	v_fmamk_f32 v156, v75, 0x3dd53b94, v140
	v_fmamk_f32 v157, v76, 0x3dd53b94, v140
	v_fmamk_f32 v158, v77, 0x3dd53b94, v140
	v_fmamk_f32 v159, v78, 0x3dd53b94, v140
	v_fmamk_f32 v160, v79, 0x3dd53b94, v140
	v_fmamk_f32 v161, v80, 0x3dd53b94, v140
	v_fmac_f32_e32 v140, 0x3dd53b94, v81
	s_waitcnt lgkmcnt(0)
	s_barrier
	v_cmp_lt_i32_e32 vcc, s17, v193
	s_and_saveexec_b64 s[12:13], vcc
	s_cbranch_execnz .Lmy_qk2_vis
	s_or_b64 exec, exec, s[12:13]
	v_mov_b32_e32 v66, 0xf149f2ca
	v_mov_b32_e32 v67, 0xf149f2ca
	v_mov_b32_e32 v68, 0xf149f2ca
	v_mov_b32_e32 v69, 0xf149f2ca
	v_mov_b32_e32 v70, 0xf149f2ca
	v_mov_b32_e32 v71, 0xf149f2ca
	v_mov_b32_e32 v72, 0xf149f2ca
	v_mov_b32_e32 v73, 0xf149f2ca
	v_mov_b32_e32 v74, 0xf149f2ca
	v_mov_b32_e32 v75, 0xf149f2ca
	v_mov_b32_e32 v76, 0xf149f2ca
	v_mov_b32_e32 v77, 0xf149f2ca
	v_mov_b32_e32 v78, 0xf149f2ca
	v_mov_b32_e32 v79, 0xf149f2ca
	v_mov_b32_e32 v80, 0xf149f2ca
	v_mov_b32_e32 v81, 0xf149f2ca
	v_mov_b32_e32 v82, 0xf149f2ca
	v_mov_b32_e32 v83, 0xf149f2ca
	v_mov_b32_e32 v84, 0xf149f2ca
	v_mov_b32_e32 v85, 0xf149f2ca
	v_mov_b32_e32 v86, 0xf149f2ca
	v_mov_b32_e32 v87, 0xf149f2ca
	v_mov_b32_e32 v88, 0xf149f2ca
	v_mov_b32_e32 v89, 0xf149f2ca
	v_mov_b32_e32 v90, 0xf149f2ca
	v_mov_b32_e32 v91, 0xf149f2ca
	v_mov_b32_e32 v92, 0xf149f2ca
	v_mov_b32_e32 v93, 0xf149f2ca
	v_mov_b32_e32 v94, 0xf149f2ca
	v_mov_b32_e32 v95, 0xf149f2ca
	v_mov_b32_e32 v96, 0xf149f2ca
	v_mov_b32_e32 v97, 0xf149f2ca
	s_branch .LBB0_711
.Lmy_qk2_vis:
	ds_read_b128 v[162:165], v185 offset:32768
	ds_read_b128 v[208:211], v185 offset:45056
	ds_read_b128 v[212:215], v186 offset:32768
	ds_read_b128 v[216:219], v186 offset:45056
	ds_read_b128 v[220:223], v188 offset:32768
	ds_read_b128 v[228:231], v188 offset:45056
	s_waitcnt lgkmcnt(5)
	v_mfma_f32_32x32x16_bf16 v[66:81], v[162:165], v[126:129], 0
	ds_read_b128 v[232:235], v187 offset:32768
	s_waitcnt lgkmcnt(5)
	v_mfma_f32_32x32x16_bf16 v[82:97], v[208:211], v[126:129], 0
	ds_read_b128 v[162:165], v187 offset:45056
	s_waitcnt lgkmcnt(5)
	v_mfma_f32_32x32x16_bf16 v[66:81], v[212:215], v[122:125], v[66:81]
	ds_read_b128 v[208:211], v185 offset:32896
	s_waitcnt lgkmcnt(5)
	v_mfma_f32_32x32x16_bf16 v[82:97], v[216:219], v[122:125], v[82:97]
	ds_read_b128 v[212:215], v185 offset:45184
	s_waitcnt lgkmcnt(5)
	v_mfma_f32_32x32x16_bf16 v[66:81], v[220:223], v[118:121], v[66:81]
	ds_read_b128 v[216:219], v186 offset:32896
	s_waitcnt lgkmcnt(5)
	v_mfma_f32_32x32x16_bf16 v[82:97], v[228:231], v[118:121], v[82:97]
	ds_read_b128 v[220:223], v186 offset:45184
	s_waitcnt lgkmcnt(5)
	v_mfma_f32_32x32x16_bf16 v[66:81], v[232:235], v[114:117], v[66:81]
	ds_read_b128 v[228:231], v188 offset:32896
	s_waitcnt lgkmcnt(5)
	v_mfma_f32_32x32x16_bf16 v[82:97], v[162:165], v[114:117], v[82:97]
	ds_read_b128 v[232:235], v188 offset:45184
	ds_read_b128 v[236:239], v183
	s_waitcnt lgkmcnt(6)
	v_mfma_f32_32x32x16_bf16 v[66:81], v[208:211], v[110:113], v[66:81]
	ds_read_b128 v[162:165], v187 offset:32896
	s_waitcnt lgkmcnt(6)
	v_mfma_f32_32x32x16_bf16 v[82:97], v[212:215], v[110:113], v[82:97]
	ds_read_b128 v[208:211], v187 offset:45184
	ds_read_b128 v[240:243], v183 offset:32
	s_waitcnt lgkmcnt(7)
	v_mfma_f32_32x32x16_bf16 v[66:81], v[216:219], v[106:109], v[66:81]
	ds_read_b128 v[212:215], v185 offset:33024
	s_waitcnt lgkmcnt(7)
	v_mfma_f32_32x32x16_bf16 v[82:97], v[220:223], v[106:109], v[82:97]
	ds_read_b128 v[216:219], v185 offset:45312
	ds_read_b128 v[244:247], v183 offset:64
	s_waitcnt lgkmcnt(8)
	v_mfma_f32_32x32x16_bf16 v[66:81], v[228:231], v[102:105], v[66:81]
	ds_read_b128 v[220:223], v186 offset:33024
	s_waitcnt lgkmcnt(8)
	v_mfma_f32_32x32x16_bf16 v[82:97], v[232:235], v[102:105], v[82:97]
	ds_read_b128 v[228:231], v186 offset:45312
	s_waitcnt lgkmcnt(7)
	v_mfma_f32_32x32x16_bf16 v[66:81], v[162:165], v[98:101], v[66:81]
	ds_read_b128 v[232:235], v188 offset:33024
	s_waitcnt lgkmcnt(7)
	v_mfma_f32_32x32x16_bf16 v[82:97], v[208:211], v[98:101], v[82:97]
	ds_read_b128 v[162:165], v188 offset:45312
	s_waitcnt lgkmcnt(6)
	v_mfma_f32_32x32x16_bf16 v[66:81], v[212:215], v[236:239], v[66:81]
	ds_read_b128 v[208:211], v187 offset:33024
	s_waitcnt lgkmcnt(6)
	v_mfma_f32_32x32x16_bf16 v[82:97], v[216:219], v[236:239], v[82:97]
	ds_read_b128 v[212:215], v187 offset:45312
	ds_read_b128 v[236:239], v183 offset:96
	s_waitcnt lgkmcnt(6)
	v_mfma_f32_32x32x16_bf16 v[66:81], v[220:223], v[240:243], v[66:81]
	s_waitcnt lgkmcnt(5)
	v_mfma_f32_32x32x16_bf16 v[82:97], v[228:231], v[240:243], v[82:97]
	s_waitcnt lgkmcnt(4)
	v_mfma_f32_32x32x16_bf16 v[66:81], v[232:235], v[244:247], v[66:81]
	s_waitcnt lgkmcnt(3)
	v_mfma_f32_32x32x16_bf16 v[82:97], v[162:165], v[244:247], v[82:97]
	s_waitcnt lgkmcnt(0)
	v_mfma_f32_32x32x16_bf16 v[66:81], v[208:211], v[236:239], v[66:81]
	s_waitcnt lgkmcnt(0)
	v_mfma_f32_32x32x16_bf16 v[82:97], v[212:215], v[236:239], v[82:97]
.LBB0_711:
	s_or_b64 exec, exec, s[12:13]
	v_exp_f32_e32 v162, v150
	v_add_f32_e32 v150, 0, v133
	v_add_f32_e32 v150, v136, v150
	v_add_f32_e32 v150, v137, v150
	v_add_f32_e32 v150, v141, v150
	v_add_f32_e32 v150, v142, v150
	v_add_f32_e32 v150, v144, v150
	v_add_f32_e32 v150, v145, v150
	v_add_f32_e32 v150, v146, v150
	v_add_f32_e32 v150, v130, v150
	v_add_f32_e32 v150, v131, v150
	v_add_f32_e32 v150, v132, v150
	v_add_f32_e32 v150, v134, v150
	v_exp_f32_e32 v147, v147
	v_add_f32_e32 v150, v135, v150
	v_exp_f32_e32 v148, v148
	v_add_f32_e32 v150, v138, v150
	v_exp_f32_e32 v149, v149
	v_add_f32_e32 v150, v139, v150
	v_add_f32_e32 v150, v143, v150
	v_exp_f32_e32 v163, v151
	v_add_f32_e32 v150, v147, v150
	v_exp_f32_e32 v164, v152
	v_add_f32_e32 v150, v148, v150
	v_exp_f32_e32 v165, v153
	v_add_f32_e32 v150, v149, v150
	v_exp_f32_e32 v210, v154
	v_add_f32_e32 v150, v162, v150
	v_exp_f32_e32 v211, v155
	v_add_f32_e32 v150, v163, v150
	v_exp_f32_e32 v212, v156
	v_add_f32_e32 v150, v164, v150
	v_exp_f32_e32 v213, v157
	v_add_f32_e32 v150, v165, v150
	v_exp_f32_e32 v214, v158
	v_add_f32_e32 v150, v210, v150
	v_exp_f32_e32 v215, v159
	v_add_f32_e32 v150, v211, v150
	v_exp_f32_e32 v216, v160
	v_add_f32_e32 v150, v212, v150
	v_exp_f32_e32 v217, v161
	v_add_f32_e32 v150, v213, v150
	v_exp_f32_e32 v140, v140
	v_add_f32_e32 v150, v214, v150
	v_add_f32_e32 v150, v215, v150
	v_add_f32_e32 v150, v216, v150
	v_add_f32_e32 v150, v217, v150
	v_add_f32_e32 v208, v140, v150
	v_mov_b32_e32 v209, v208
	v_cvt_pk_bf16_f32 v150, v133, v136
	v_cvt_pk_bf16_f32 v151, v137, v141
	v_cvt_pk_bf16_f32 v152, v142, v144
	v_cvt_pk_bf16_f32 v153, v145, v146
	v_cvt_pk_bf16_f32 v154, v130, v131
	v_cvt_pk_bf16_f32 v155, v132, v134
	v_cvt_pk_bf16_f32 v156, v135, v138
	v_cvt_pk_bf16_f32 v157, v139, v143
	v_cvt_pk_bf16_f32 v158, v147, v148
	v_cvt_pk_bf16_f32 v159, v149, v162
	v_cvt_pk_bf16_f32 v160, v163, v164
	v_cvt_pk_bf16_f32 v161, v165, v210
	v_cvt_pk_bf16_f32 v162, v211, v212
	v_cvt_pk_bf16_f32 v163, v213, v214
	v_cvt_pk_bf16_f32 v164, v215, v216
	v_cvt_pk_bf16_f32 v165, v217, v140
	v_permlane32_swap_b32_e32 v208, v209
	v_permlane32_swap_b32_e32 v150, v152
	v_permlane32_swap_b32_e32 v151, v153
	v_permlane32_swap_b32_e32 v154, v156
	v_permlane32_swap_b32_e32 v155, v157
	v_permlane32_swap_b32_e32 v158, v160
	v_permlane32_swap_b32_e32 v159, v161
	v_permlane32_swap_b32_e32 v162, v164
	v_permlane32_swap_b32_e32 v163, v165
	v_add_u32_e32 v130, 0xc0, v205
	v_add_u32_e32 v132, 0xe0, v205
	v_ashrrev_i32_e32 v131, 31, v130
	v_ashrrev_i32_e32 v133, 31, v132
	v_add_u32_e32 v146, 0xc0, v207
	v_lshlrev_b64 v[138:139], 11, v[130:131]
	v_lshlrev_b64 v[140:141], 11, v[132:133]
	v_ashrrev_i32_e32 v147, 31, v146
	v_or_b32_e32 v138, v138, v206
	v_or_b32_e32 v140, v140, v206
	v_lshlrev_b64 v[146:147], 7, v[146:147]
	v_lshl_add_u64 v[130:131], s[14:15], 0, v[138:139]
	v_lshl_add_u64 v[134:135], s[14:15], 0, v[140:141]
	v_lshl_add_u64 v[138:139], s[64:65], 0, v[138:139]
	v_lshl_add_u64 v[142:143], s[64:65], 0, v[140:141]
	v_lshl_add_u64 v[146:147], v[178:179], 0, v[146:147]
	global_load_dwordx4 v[130:133], v[130:131], off
	s_nop 0
	global_load_dwordx4 v[134:137], v[134:135], off
	s_nop 0
	global_load_dwordx4 v[138:141], v[138:139], off
	s_nop 0
	global_load_dwordx4 v[142:145], v[142:143], off
	s_nop 0
	global_load_dwordx4 v[146:149], v[146:147], off
	s_and_saveexec_b64 s[12:13], s[10:11]
	s_cbranch_execz .LBB0_713
	ds_read_b64_tr_b16 v[210:211], v177
	ds_read_b64_tr_b16 v[212:213], v177 offset:2048
	ds_read_b64_tr_b16 v[214:215], v177 offset:4096
	ds_read_b64_tr_b16 v[216:217], v177 offset:6144
	ds_read_b64_tr_b16 v[218:219], v177 offset:8192
	ds_read_b64_tr_b16 v[220:221], v177 offset:10240
	ds_read_b64_tr_b16 v[222:223], v177 offset:12288
	ds_read_b64_tr_b16 v[224:225], v177 offset:14336
	s_waitcnt lgkmcnt(6)
	s_nop 0
	v_mfma_f32_32x32x16_bf16 v[2:17], v[150:153], v[210:213], v[2:17]
	ds_read_b64_tr_b16 v[228:229], v177 offset:512
	ds_read_b64_tr_b16 v[230:231], v177 offset:2560
	s_waitcnt lgkmcnt(6)
	v_mfma_f32_32x32x16_bf16 v[2:17], v[154:157], v[214:217], v[2:17]
	ds_read_b64_tr_b16 v[210:211], v177 offset:4608
	ds_read_b64_tr_b16 v[212:213], v177 offset:6656
	s_waitcnt lgkmcnt(6)
	v_mfma_f32_32x32x16_bf16 v[2:17], v[158:161], v[218:221], v[2:17]
	ds_read_b64_tr_b16 v[214:215], v177 offset:8704
	ds_read_b64_tr_b16 v[216:217], v177 offset:10752
	s_waitcnt lgkmcnt(6)
	v_mfma_f32_32x32x16_bf16 v[2:17], v[162:165], v[222:225], v[2:17]
	ds_read_b64_tr_b16 v[218:219], v177 offset:12800
	ds_read_b64_tr_b16 v[220:221], v177 offset:14848
	s_waitcnt lgkmcnt(6)
	v_mfma_f32_32x32x16_bf16 v[50:65], v[150:153], v[228:231], v[50:65]
	ds_read_b64_tr_b16 v[222:223], v177 offset:1024
	ds_read_b64_tr_b16 v[224:225], v177 offset:3072
	s_waitcnt lgkmcnt(6)
	v_mfma_f32_32x32x16_bf16 v[50:65], v[154:157], v[210:213], v[50:65]
	ds_read_b64_tr_b16 v[228:229], v177 offset:5120
	ds_read_b64_tr_b16 v[230:231], v177 offset:7168
	s_waitcnt lgkmcnt(6)
	v_mfma_f32_32x32x16_bf16 v[50:65], v[158:161], v[214:217], v[50:65]
	ds_read_b64_tr_b16 v[210:211], v177 offset:9216
	ds_read_b64_tr_b16 v[212:213], v177 offset:11264
	s_waitcnt lgkmcnt(6)
	v_mfma_f32_32x32x16_bf16 v[50:65], v[162:165], v[218:221], v[50:65]
	ds_read_b64_tr_b16 v[214:215], v177 offset:13312
	ds_read_b64_tr_b16 v[216:217], v177 offset:15360
	s_waitcnt lgkmcnt(6)
	v_mfma_f32_32x32x16_bf16 v[34:49], v[150:153], v[222:225], v[34:49]
	ds_read_b64_tr_b16 v[218:219], v177 offset:1536
	ds_read_b64_tr_b16 v[220:221], v177 offset:3584
	s_waitcnt lgkmcnt(6)
	v_mfma_f32_32x32x16_bf16 v[34:49], v[154:157], v[228:231], v[34:49]
	ds_read_b64_tr_b16 v[222:223], v177 offset:5632
	ds_read_b64_tr_b16 v[224:225], v177 offset:7680
	s_waitcnt lgkmcnt(6)
	v_mfma_f32_32x32x16_bf16 v[34:49], v[158:161], v[210:213], v[34:49]
	ds_read_b64_tr_b16 v[228:229], v177 offset:9728
	ds_read_b64_tr_b16 v[230:231], v177 offset:11776
	s_waitcnt lgkmcnt(6)
	v_mfma_f32_32x32x16_bf16 v[34:49], v[162:165], v[214:217], v[34:49]
	ds_read_b64_tr_b16 v[210:211], v177 offset:13824
	ds_read_b64_tr_b16 v[212:213], v177 offset:15872
	s_waitcnt lgkmcnt(6)
	v_mfma_f32_32x32x16_bf16 v[18:33], v[150:153], v[218:221], v[18:33]
	s_waitcnt lgkmcnt(4)
	v_mfma_f32_32x32x16_bf16 v[18:33], v[154:157], v[222:225], v[18:33]
	s_waitcnt lgkmcnt(2)
	v_mfma_f32_32x32x16_bf16 v[18:33], v[158:161], v[228:231], v[18:33]
	s_waitcnt lgkmcnt(0)
	v_mfma_f32_32x32x16_bf16 v[18:33], v[162:165], v[210:213], v[18:33]

.LBB0_717:
	v_cndmask_b32_e64 v201, v151, v201, s[10:11]
	v_mul_f32_e32 v140, 0xbdd53b94, v201
	v_mov_b32_e32 v141, v140
	v_fmamk_f32 v66, v66, 0x3dd53b94, v140
	v_fmamk_f32 v67, v67, 0x3dd53b94, v140
	v_fmamk_f32 v68, v68, 0x3dd53b94, v140
	v_fmamk_f32 v69, v69, 0x3dd53b94, v140
	v_fmamk_f32 v70, v70, 0x3dd53b94, v140
	v_fmamk_f32 v71, v71, 0x3dd53b94, v140
	v_fmamk_f32 v72, v72, 0x3dd53b94, v140
	v_fmamk_f32 v73, v73, 0x3dd53b94, v140
	v_fmamk_f32 v74, v74, 0x3dd53b94, v140
	v_fmamk_f32 v75, v75, 0x3dd53b94, v140
	v_fmamk_f32 v76, v76, 0x3dd53b94, v140
	v_fmamk_f32 v77, v77, 0x3dd53b94, v140
	v_fmamk_f32 v78, v78, 0x3dd53b94, v140
	v_fmamk_f32 v79, v79, 0x3dd53b94, v140
	v_fmamk_f32 v80, v80, 0x3dd53b94, v140
	v_fmac_f32_e32 v141, 0x3dd53b94, v81
	v_exp_f32_e32 v146, v66
	v_exp_f32_e32 v147, v67
	v_exp_f32_e32 v148, v68
	v_exp_f32_e32 v149, v69
	v_exp_f32_e32 v154, v70
	v_exp_f32_e32 v160, v71
	v_exp_f32_e32 v161, v72
	v_exp_f32_e32 v162, v73
	v_exp_f32_e32 v151, v74
	v_exp_f32_e32 v152, v75
	v_exp_f32_e32 v153, v76
	v_exp_f32_e32 v155, v77
	v_exp_f32_e32 v156, v78
	v_exp_f32_e32 v157, v79
	v_exp_f32_e32 v158, v80
	v_exp_f32_e32 v159, v141
	v_add_f32_e32 v66, v202, v203
	v_fmac_f32_e32 v66, v199, v173
	v_add_f32_e32 v173, v208, v209
	s_addk_i32 s16, 0x80
	s_add_i32 s91, s91, 2
	v_fmamk_f32 v138, v82, 0x3dd53b94, v140
	v_fmamk_f32 v139, v83, 0x3dd53b94, v140
	v_fmamk_f32 v136, v84, 0x3dd53b94, v140
	v_fmamk_f32 v137, v85, 0x3dd53b94, v140
	v_fmamk_f32 v134, v86, 0x3dd53b94, v140
	v_fmamk_f32 v135, v87, 0x3dd53b94, v140
	v_fmamk_f32 v132, v88, 0x3dd53b94, v140
	v_fmamk_f32 v133, v89, 0x3dd53b94, v140
	v_fmamk_f32 v130, v90, 0x3dd53b94, v140
	v_fmamk_f32 v131, v91, 0x3dd53b94, v140
	v_fmamk_f32 v144, v92, 0x3dd53b94, v140
	v_fmamk_f32 v145, v93, 0x3dd53b94, v140
	v_fmamk_f32 v142, v94, 0x3dd53b94, v140
	v_fmamk_f32 v143, v95, 0x3dd53b94, v140
	v_fmamk_f32 v141, v97, 0x3dd53b94, v140
	v_fmac_f32_e32 v140, 0x3dd53b94, v96
	v_fmac_f32_e32 v173, v66, v204
	s_cmp_ge_u32 s91, s92
	s_waitcnt lgkmcnt(0)
	s_barrier
	s_cbranch_scc1 .LBB0_719
	v_mov_b32_e32 v199, v150
	s_branch .LBB0_701
